# tree-shaped v_max3 reduction (depth 3 instead of 8-deep serial chain) in diff-attention tile loop, on top of v12
# speedup vs baseline: 1.0013x; 1.0013x over previous
; #define LAS __attribute__((address_space(3)))
; __device__ __forceinline__ float max3f(float a, float b, float c) { float r; asm("v_max3_f32 %0, %1, %2, %3" : "=v"(r) : "v"(a), "v"(b), "v"(c)); return r; }
; #define MFMA16(a, b, c) __builtin_amdgcn_mfma_f32_16x16x32_bf16((a), (b), (c), 0, 0, 0)
; template <int NS, int DV, class MaskF> ...
;     ...
; #pragma unroll
;     for (int st = 0; st < NS; ++st)
; #pragma unroll
;         for (int kt = 0; kt < 4; ++kt) {
;             const LAS unsigned char* kp = bufK + (kslot[st] * 64 + kt * 16 + fr) * AT_PITCH + g * 16;
;             const bf16x8 a0 = *(const LAS bf16x8*)kp, a1 = *(const LAS bf16x8*)(kp + 64);
;             const float nm = -mrun[st];
;             f32x4 z = {nm, nm, nm, nm};
;             z = MFMA16(a0, qf[st][0], z); z = MFMA16(a1, qf[st][1], z);
;             s[st][kt] = z;
;         }
;     ...
;     float mxs[NS]; bool slow = first;
; #pragma unroll
;     for (int st = 0; st < NS; ++st) {
;         float mx = max3f(s[st][0][0], s[st][0][1], s[st][0][2]);
;         mx = max3f(mx, s[st][0][3], s[st][1][0]); mx = max3f(mx, s[st][1][1], s[st][1][2]); mx = max3f(mx, s[st][1][3], s[st][2][0]);
;         mx = max3f(mx, s[st][2][1], s[st][2][2]); mx = max3f(mx, s[st][2][3], s[st][3][0]); mx = max3f(mx, s[st][3][1], s[st][3][2]); mx = max3f(mx, s[st][3][3], mx);
;         mx = max3f(mx, __shfl_xor(mx, 16), mx); mx = max3f(mx, __shfl_xor(mx, 32), mx);
;         mxs[st] = mx; slow = slow || (mx > 8.0f);
;     }
;     if (__any(slow)) {
.LBB0_650:
	s_mul_i32 s14, s13, 0xa000
	v_add_u32_e32 v190, s14, v227
	ds_read_b128 v[146:149], v190
	ds_read_b128 v[150:153], v190 offset:64
	ds_read_b128 v[154:157], v190 offset:2560
	ds_read_b128 v[158:161], v190 offset:2624
	ds_read_b128 v[182:185], v190 offset:5120
	ds_read_b128 v[186:189], v190 offset:5184
	v_xor_b32_e32 v126, 0x80000000, v173
	v_xor_b32_e32 v138, 0x80000000, v172
	v_mov_b32_e32 v127, v126
	v_mov_b32_e32 v128, v126
	v_mov_b32_e32 v129, v126
	v_mov_b32_e32 v139, v138
	v_mov_b32_e32 v140, v138
	v_mov_b32_e32 v141, v138
	s_mul_i32 s15, s15, 0xa000
	s_add_i32 s15, s15, 0
	s_waitcnt lgkmcnt(5)
	v_mfma_f32_16x16x32_bf16 v[114:117], v[146:149], v[2:5], v[126:129]
	ds_read_b128 v[146:149], v190 offset:7680
	s_waitcnt lgkmcnt(5)
	v_mfma_f32_16x16x32_bf16 v[114:117], v[150:153], v[6:9], v[114:117]
	ds_read_b128 v[150:153], v190 offset:7744
	s_waitcnt lgkmcnt(5)
	v_mfma_f32_16x16x32_bf16 v[118:121], v[154:157], v[2:5], v[126:129]
	ds_read_b128 v[154:157], v190 offset:10240
	s_waitcnt lgkmcnt(5)
	v_mfma_f32_16x16x32_bf16 v[118:121], v[158:161], v[6:9], v[118:121]
	ds_read_b128 v[158:161], v190 offset:10304
	s_waitcnt lgkmcnt(5)
	v_mfma_f32_16x16x32_bf16 v[122:125], v[182:185], v[2:5], v[126:129]
	ds_read_b128 v[182:185], v190 offset:12800
	s_waitcnt lgkmcnt(5)
	v_mfma_f32_16x16x32_bf16 v[122:125], v[186:189], v[6:9], v[122:125]
	ds_read_b128 v[186:189], v190 offset:12864
	s_waitcnt lgkmcnt(5)
	v_mfma_f32_16x16x32_bf16 v[126:129], v[146:149], v[2:5], v[126:129]
	ds_read_b128 v[146:149], v190 offset:15360
	s_waitcnt lgkmcnt(5)
	v_mfma_f32_16x16x32_bf16 v[126:129], v[150:153], v[6:9], v[126:129]
	ds_read_b128 v[150:153], v190 offset:15424
	s_waitcnt lgkmcnt(5)
	v_mfma_f32_16x16x32_bf16 v[134:137], v[154:157], v[10:13], v[138:141]
	ds_read_b128 v[154:157], v190 offset:17920
	s_waitcnt lgkmcnt(5)
	v_mfma_f32_16x16x32_bf16 v[134:137], v[158:161], v[14:17], v[134:137]
	ds_read_b128 v[158:161], v190 offset:17984
	s_waitcnt lgkmcnt(5)
	v_mfma_f32_16x16x32_bf16 v[142:145], v[182:185], v[10:13], v[138:141]
	s_waitcnt lgkmcnt(4)
	v_mfma_f32_16x16x32_bf16 v[142:145], v[186:189], v[14:17], v[142:145]
	s_waitcnt lgkmcnt(3)
	v_mfma_f32_16x16x32_bf16 v[130:133], v[146:149], v[10:13], v[138:141]
	s_waitcnt lgkmcnt(2)
	v_mfma_f32_16x16x32_bf16 v[130:133], v[150:153], v[14:17], v[130:133]
	s_waitcnt lgkmcnt(1)
	v_mfma_f32_16x16x32_bf16 v[138:141], v[154:157], v[10:13], v[138:141]
	s_waitcnt lgkmcnt(0)
	v_mfma_f32_16x16x32_bf16 v[138:141], v[158:161], v[14:17], v[138:141]
	v_max3_f32 v146, v114, v115, v116
	v_max3_f32 v147, v117, v118, v119
	s_mov_b32 s16, 0x41000000
	v_max3_f32 v184, v120, v121, v122
	v_max3_f32 v185, v123, v124, v125
	v_add3_u32 v179, s15, v226, v0
	v_max3_f32 v186, v126, v127, v128
	v_max3_f32 v148, v134, v135, v136
	v_add3_u32 v180, s15, v225, v0
	v_max3_f32 v146, v146, v147, v184
	v_max3_f32 v185, v185, v186, v129
	v_add3_u32 v178, s15, v224, v0
	v_max3_f32 v149, v137, v142, v143
	v_max_f32_e32 v146, v146, v185
	v_max3_f32 v187, v144, v145, v130
	v_max3_f32 v182, v131, v132, v133
	v_max3_f32 v148, v148, v149, v187
	s_nop 1
	v_max3_f32 v183, v138, v139, v140
	s_nop 0
	v_max3_f32 v182, v182, v183, v141
	s_nop 0
	v_max_f32_e32 v148, v148, v182
	v_mov_b32_e32 v147, v146
	v_mov_b32_e32 v149, v148
	s_nop 1
	v_permlane16_swap_b32_e32 v146, v147
	v_permlane16_swap_b32_e32 v148, v149
	v_max_f32_e32 v146, v146, v147
	v_max_f32_e32 v148, v148, v149
	v_mov_b32_e32 v147, v146
	v_mov_b32_e32 v149, v148
	s_nop 1
	v_permlane32_swap_b32_e32 v146, v147
	v_permlane32_swap_b32_e32 v148, v149
	v_max_f32_e32 v147, v146, v147
	v_max_f32_e32 v146, v148, v149
	s_nop 0
	v_max_f32_e32 v148, v146, v146
	v_max_f32_e32 v149, v147, v147
	v_max_f32_e32 v150, v149, v148
	v_cmp_lt_f32_e32 vcc, s16, v150
	s_cbranch_vccz .LBB0_652
; #define LAS __attribute__((address_space(3)))
; __device__ __forceinline__ float ex2(float x) { return __builtin_amdgcn_exp2f(x); }
; #define MFMA16(a, b, c) __builtin_amdgcn_mfma_f32_16x16x32_bf16((a), (b), (c), 0, 0, 0)
; template <int NS, int DV, class MaskF> ...
;     ...
;     if (__any(slow)) {
; #pragma unroll
;         for (int dt = 0; dt < DV / 16; ++dt)
; #pragma unroll
;             for (int j = 0; j < 2; ++j) {
;                 const bf16x8 va = *(const LAS bf16x8*)(bufV + (128 + vrow0 + dt * 16 + fr) * AT_PITCH + (j * 32 + g * 8) * 2);
; #pragma unroll
;                 for (int st = 0; st < NS; ++st) o[st][dt] = MFMA16(va, pkp[st][j], o[st][dt]);
;             }
; #pragma unroll
;         for (int st = 0; st < NS; ++st) {
;             const float d = mxs[st] < -1e20f ? 0.f : (first ? mxs[st] : fmaxf(mxs[st], 0.f));
;             mrun[st] += d; const float alpha = ex2(-d);
;             lrun[st] *= alpha;
; #pragma unroll
;             for (int kt = 0; kt < 4; ++kt) s[st][kt] = s[st][kt] - d;
; #pragma unroll
;             for (int dt = 0; dt < DV / 16; ++dt) o[st][dt] = o[st][dt] * alpha;
;             pkp[st][0] = (bf16x8){0, 0, 0, 0, 0, 0, 0, 0}; pkp[st][1] = pkp[st][0];
;         }
;     }
	ds_read_b128 v[150:153], v179 offset:20480
	s_mov_b32 s15, 0xe0ad78ec
	v_cmp_ngt_f32_e32 vcc, s15, v147
	s_waitcnt lgkmcnt(0)
	v_mfma_f32_16x16x32_bf16 v[38:41], v[150:153], v[54:57], v[38:41]
	v_mfma_f32_16x16x32_bf16 v[78:81], v[150:153], v[98:101], v[78:81]
	ds_read_b128 v[150:153], v179 offset:20544
	s_waitcnt lgkmcnt(0)
	v_mfma_f32_16x16x32_bf16 v[38:41], v[150:153], v[46:49], v[38:41]
	v_mfma_f32_16x16x32_bf16 v[78:81], v[150:153], v[70:73], v[78:81]
	ds_read_b128 v[150:153], v179 offset:23040
	s_waitcnt lgkmcnt(0)
	v_mfma_f32_16x16x32_bf16 v[34:37], v[150:153], v[54:57], v[34:37]
	v_mfma_f32_16x16x32_bf16 v[74:77], v[150:153], v[98:101], v[74:77]
	ds_read_b128 v[150:153], v179 offset:23104
	s_waitcnt lgkmcnt(0)
	v_mfma_f32_16x16x32_bf16 v[34:37], v[150:153], v[46:49], v[34:37]
	v_mfma_f32_16x16x32_bf16 v[74:77], v[150:153], v[70:73], v[74:77]
	ds_read_b128 v[150:153], v179 offset:25600
	s_waitcnt lgkmcnt(0)
	v_mfma_f32_16x16x32_bf16 v[42:45], v[150:153], v[54:57], v[42:45]
	v_mfma_f32_16x16x32_bf16 v[82:85], v[150:153], v[98:101], v[82:85]
	ds_read_b128 v[150:153], v179 offset:25664
	s_waitcnt lgkmcnt(0)
	v_mfma_f32_16x16x32_bf16 v[42:45], v[150:153], v[46:49], v[42:45]
	v_mfma_f32_16x16x32_bf16 v[82:85], v[150:153], v[70:73], v[82:85]
	ds_read_b128 v[150:153], v180 offset:20480
	s_waitcnt lgkmcnt(0)
	v_mfma_f32_16x16x32_bf16 v[50:53], v[150:153], v[54:57], v[50:53]
	v_mfma_f32_16x16x32_bf16 v[86:89], v[150:153], v[98:101], v[86:89]
	ds_read_b128 v[150:153], v180 offset:20544
	s_waitcnt lgkmcnt(0)
	v_mfma_f32_16x16x32_bf16 v[50:53], v[150:153], v[46:49], v[50:53]
	v_mfma_f32_16x16x32_bf16 v[86:89], v[150:153], v[70:73], v[86:89]
	ds_read_b128 v[150:153], v179 offset:30720
	s_waitcnt lgkmcnt(0)
	v_mfma_f32_16x16x32_bf16 v[62:65], v[150:153], v[54:57], v[62:65]
	v_mfma_f32_16x16x32_bf16 v[94:97], v[150:153], v[98:101], v[94:97]
	ds_read_b128 v[150:153], v179 offset:30784
	s_waitcnt lgkmcnt(0)
	v_mfma_f32_16x16x32_bf16 v[62:65], v[150:153], v[46:49], v[62:65]
	v_mfma_f32_16x16x32_bf16 v[94:97], v[150:153], v[70:73], v[94:97]
	ds_read_b128 v[150:153], v179 offset:33280
	s_waitcnt lgkmcnt(0)
	v_mfma_f32_16x16x32_bf16 v[58:61], v[150:153], v[54:57], v[58:61]
	v_mfma_f32_16x16x32_bf16 v[90:93], v[150:153], v[98:101], v[90:93]
	ds_read_b128 v[150:153], v179 offset:33344
	s_waitcnt lgkmcnt(0)
	v_mfma_f32_16x16x32_bf16 v[58:61], v[150:153], v[46:49], v[58:61]
	v_mfma_f32_16x16x32_bf16 v[90:93], v[150:153], v[70:73], v[90:93]
	ds_read_b128 v[150:153], v179 offset:35840
	s_waitcnt lgkmcnt(0)
	v_mfma_f32_16x16x32_bf16 v[66:69], v[150:153], v[54:57], v[66:69]
	v_mfma_f32_16x16x32_bf16 v[102:105], v[150:153], v[98:101], v[102:105]
	ds_read_b128 v[150:153], v179 offset:35904
	s_waitcnt lgkmcnt(0)
	v_mfma_f32_16x16x32_bf16 v[66:69], v[150:153], v[46:49], v[66:69]
	v_mfma_f32_16x16x32_bf16 v[102:105], v[150:153], v[70:73], v[102:105]
	ds_read_b128 v[150:153], v178 offset:20480
	s_waitcnt lgkmcnt(0)
	v_mfma_f32_16x16x32_bf16 v[54:57], v[150:153], v[54:57], v[106:109]
	s_nop 2
	ds_read_b128 v[106:109], v178 offset:20544
	v_mfma_f32_16x16x32_bf16 v[98:101], v[150:153], v[98:101], v[110:113]
	s_waitcnt lgkmcnt(0)
	v_mfma_f32_16x16x32_bf16 v[54:57], v[106:109], v[46:49], v[54:57]
	v_mfma_f32_16x16x32_bf16 v[46:49], v[106:109], v[70:73], v[98:101]
	v_max_f32_e32 v70, 0, v149
	v_max_f32_e32 v72, 0, v148
	v_cndmask_b32_e32 v71, 0, v70, vcc
	v_cmp_ngt_f32_e32 vcc, s15, v146
	v_sub_f32_e32 v114, v114, v71
	v_sub_f32_e32 v115, v115, v71
	v_cndmask_b32_e32 v70, 0, v72, vcc
	v_exp_f32_e64 v72, -v71
	v_pk_add_f32 v[172:173], v[172:173], v[70:71]
	v_sub_f32_e32 v134, v134, v70
	v_sub_f32_e32 v135, v135, v70
	v_pk_mul_f32 v[106:107], v[72:73], v[54:55] op_sel_hi:[0,1]
	v_exp_f32_e64 v54, -v70
	v_mov_b32_e32 v55, v72
	v_sub_f32_e32 v136, v136, v70
	v_sub_f32_e32 v137, v137, v70
	v_sub_f32_e32 v142, v142, v70
	v_sub_f32_e32 v143, v143, v70
	v_sub_f32_e32 v144, v144, v70
	v_sub_f32_e32 v145, v145, v70
	v_sub_f32_e32 v130, v130, v70
	v_sub_f32_e32 v131, v131, v70
	v_sub_f32_e32 v132, v132, v70
	v_sub_f32_e32 v133, v133, v70
	v_sub_f32_e32 v138, v138, v70
	v_sub_f32_e32 v139, v139, v70
	v_sub_f32_e32 v140, v140, v70
	v_sub_f32_e32 v141, v141, v70
	v_mov_b32_e32 v70, 0
	v_sub_f32_e32 v116, v116, v71
	v_sub_f32_e32 v117, v117, v71
	v_sub_f32_e32 v118, v118, v71
	v_sub_f32_e32 v119, v119, v71
	v_sub_f32_e32 v120, v120, v71
	v_sub_f32_e32 v121, v121, v71
	v_sub_f32_e32 v122, v122, v71
	v_sub_f32_e32 v123, v123, v71
	v_sub_f32_e32 v124, v124, v71
	v_sub_f32_e32 v125, v125, v71
	v_sub_f32_e32 v126, v126, v71
	v_sub_f32_e32 v127, v127, v71
	v_sub_f32_e32 v128, v128, v71
	v_sub_f32_e32 v129, v129, v71
	v_pk_mul_f32 v[40:41], v[72:73], v[40:41] op_sel_hi:[0,1]
	v_pk_mul_f32 v[38:39], v[72:73], v[38:39] op_sel_hi:[0,1]
	v_pk_mul_f32 v[36:37], v[72:73], v[36:37] op_sel_hi:[0,1]
	v_pk_mul_f32 v[34:35], v[72:73], v[34:35] op_sel_hi:[0,1]
	v_pk_mul_f32 v[44:45], v[72:73], v[44:45] op_sel_hi:[0,1]
	v_pk_mul_f32 v[42:43], v[72:73], v[42:43] op_sel_hi:[0,1]
	v_pk_mul_f32 v[52:53], v[72:73], v[52:53] op_sel_hi:[0,1]
	v_pk_mul_f32 v[50:51], v[72:73], v[50:51] op_sel_hi:[0,1]
	v_pk_mul_f32 v[64:65], v[72:73], v[64:65] op_sel_hi:[0,1]
	v_pk_mul_f32 v[62:63], v[72:73], v[62:63] op_sel_hi:[0,1]
	v_pk_mul_f32 v[60:61], v[72:73], v[60:61] op_sel_hi:[0,1]
	v_pk_mul_f32 v[58:59], v[72:73], v[58:59] op_sel_hi:[0,1]
	v_pk_mul_f32 v[68:69], v[72:73], v[68:69] op_sel_hi:[0,1]
	v_pk_mul_f32 v[66:67], v[72:73], v[66:67] op_sel_hi:[0,1]
	v_pk_mul_f32 v[108:109], v[72:73], v[56:57] op_sel_hi:[0,1]
	v_pk_mul_f32 v[174:175], v[174:175], v[54:55]
	v_pk_mul_f32 v[80:81], v[54:55], v[80:81] op_sel_hi:[0,1]
	v_pk_mul_f32 v[78:79], v[54:55], v[78:79] op_sel_hi:[0,1]
	v_pk_mul_f32 v[76:77], v[54:55], v[76:77] op_sel_hi:[0,1]
	v_pk_mul_f32 v[74:75], v[54:55], v[74:75] op_sel_hi:[0,1]
	v_pk_mul_f32 v[84:85], v[54:55], v[84:85] op_sel_hi:[0,1]
	v_pk_mul_f32 v[82:83], v[54:55], v[82:83] op_sel_hi:[0,1]
	v_pk_mul_f32 v[88:89], v[54:55], v[88:89] op_sel_hi:[0,1]
	v_pk_mul_f32 v[86:87], v[54:55], v[86:87] op_sel_hi:[0,1]
	v_pk_mul_f32 v[96:97], v[54:55], v[96:97] op_sel_hi:[0,1]
	v_pk_mul_f32 v[94:95], v[54:55], v[94:95] op_sel_hi:[0,1]
	v_pk_mul_f32 v[92:93], v[54:55], v[92:93] op_sel_hi:[0,1]
	v_pk_mul_f32 v[90:91], v[54:55], v[90:91] op_sel_hi:[0,1]
	v_pk_mul_f32 v[104:105], v[54:55], v[104:105] op_sel_hi:[0,1]
	v_pk_mul_f32 v[102:103], v[54:55], v[102:103] op_sel_hi:[0,1]
	v_pk_mul_f32 v[112:113], v[54:55], v[48:49] op_sel_hi:[0,1]
	v_pk_mul_f32 v[110:111], v[54:55], v[46:47] op_sel_hi:[0,1]
	v_mov_b32_e32 v71, v70
	v_mov_b32_e32 v72, v70
	v_mov_b32_e32 v73, v70
	v_mov_b32_e32 v98, v70
	v_mov_b32_e32 v99, v70
	v_mov_b32_e32 v100, v70
	v_mov_b32_e32 v101, v70
	v_mov_b32_e32 v46, v70
	v_mov_b32_e32 v47, v70
	v_mov_b32_e32 v48, v70
	v_mov_b32_e32 v49, v70
	v_mov_b32_e32 v54, v70
	v_mov_b32_e32 v55, v70
	v_mov_b32_e32 v56, v70
	v_mov_b32_e32 v57, v70
